# norm phase: each wave walks its rows from the most recently written (context, second latent half) to the oldest, for L2 hits on x written by the preceding out-proj
# baseline (speedup 1.0000x reference)
; DI int otid() { int t = threadIdx.x; asm volatile("" : "+v"(t)); return t; }
; DI void norm_phase(const Params& p, int l) {
;     const int tid_ = otid(), lane = tid_ & 63, wave = tid_ >> 6;
;     const int gw = blockIdx.x * 4 + wave, nw = gridDim.x * 4;
;     const float* g = p.norm_g + l * D;
;     float4 gg[4];
; #pragma unroll
;     for (int j = 0; j < 4; ++j) gg[j] = *(const float4*)(g + 256 * j + 4 * lane);
;     for (int row0 = gw; row0 < NTOK; row0 += 3 * nw) {
;         float4 v[3][4];
;         const float* md[3];
; #pragma unroll
;         for (int u = 0; u < 3; ++u) {
;             const int row = row0 + u * nw;
;             const int rc = row < NTOK ? row : gw;
;             const int b = rc / TPB, t = rc % TPB;
;             const float* src = src_row(p, l, b, t);
;             md[u] = p.mod + ((size_t)l * 9 + (t < SEQ ? b : 8)) * 3072;
; #pragma unroll
;             for (int j = 0; j < 4; ++j) v[u][j] = *(const float4*)(src + 256 * j + 4 * lane);
;         }
.LBB0_137:
	s_andn2_b64 vcc, exec, s[4:5]
	s_cbranch_vccnz .LBB0_292
	s_cmp_eq_u32 s98, 1
	s_mov_b64 s[4:5], -1
	s_cbranch_scc1 .LBB0_183
	v_mov_b32_e32 v16, v200
	v_readlane_b32 s4, v254, 21
	v_readlane_b32 s100, v254, 22
	s_mov_b32 s101, 0x47ff
	s_cmp_lg_u32 s100, 0x800
	s_cbranch_scc1 .Lnorm_nomap
	s_lshr_b32 s100, s4, 5
	s_lshl_b32 s100, s100, 2
	s_bfe_u32 s4, s4, 0x30002
	s_mulk_i32 s4, 0x900
	s_mov_b32 s101, 0x7fffffff
	s_add_i32 s4, s4, s100
	s_movk_i32 s100, 0xff00
.Lnorm_nomap:
	v_ashrrev_i32_e32 v0, 6, v16
	s_nop 0
	v_add_u32_e32 v65, s4, v0
	s_movk_i32 s4, 0x4800
	v_cmp_gt_i32_e32 vcc, s4, v65
	s_and_saveexec_b64 s[62:63], vcc
	s_cbranch_execz .LBB0_182
	s_load_dwordx2 s[4:5], s[0:1], 0x20
	s_load_dwordx2 s[98:99], s[0:1], 0x10
	s_lshl_b32 s6, s60, 10
	s_ashr_i32 s7, s6, 31
	v_lshlrev_b32_e32 v17, 2, v16
	s_lshl_b64 s[6:7], s[6:7], 2
	s_waitcnt lgkmcnt(0)
	s_add_u32 s4, s4, s6
	v_and_b32_e32 v64, 0xfc, v17
	s_addc_u32 s5, s5, s7
	v_lshlrev_b32_e32 v12, 2, v64
	global_load_dwordx4 v[0:3], v12, s[4:5]
	global_load_dwordx4 v[4:7], v12, s[4:5] offset:1024
	global_load_dwordx4 v[8:11], v12, s[4:5] offset:2048
	s_nop 0
	global_load_dwordx4 v[12:15], v12, s[4:5] offset:3072
	v_and_b32_e32 v18, 64, v205
	v_add_u32_e32 v18, 64, v18
	v_xor_b32_e32 v19, 1, v205
	v_cmp_lt_i32_e32 vcc, v19, v18
	s_load_dwordx2 s[4:5], s[0:1], 0x0
	s_load_dwordx2 s[34:35], s[0:1], 0xb8
	s_load_dwordx2 s[28:29], s[0:1], 0xe0
	s_load_dwordx4 s[56:59], s[0:1], 0xa8
	v_cndmask_b32_e32 v19, v205, v19, vcc
	v_lshlrev_b32_e32 v79, 2, v19
	v_xor_b32_e32 v19, 2, v205
	v_cmp_lt_i32_e32 vcc, v19, v18
	v_bfe_u32 v17, v17, 5, 3
	v_lshlrev_b32_e32 v16, 3, v16
	v_cndmask_b32_e32 v19, v205, v19, vcc
	v_lshlrev_b32_e32 v84, 2, v19
	v_xor_b32_e32 v19, 4, v205
	v_cmp_lt_i32_e32 vcc, v19, v18
	v_readlane_b32 s6, v255, 34
	v_and_b32_e32 v192, 56, v16
	v_cndmask_b32_e32 v19, v205, v19, vcc
	v_lshlrev_b32_e32 v85, 2, v19
	v_xor_b32_e32 v19, 8, v205
	v_cmp_lt_i32_e32 vcc, v19, v18
	v_readlane_b32 s7, v255, 35
	s_cmp_gt_u32 s6, 4
	v_cndmask_b32_e32 v19, v205, v19, vcc
	v_lshlrev_b32_e32 v86, 2, v19
	v_xor_b32_e32 v19, 16, v205
	v_cmp_lt_i32_e32 vcc, v19, v18
	s_cselect_b64 s[6:7], -1, 0
	s_mul_hi_i32 s9, s60, 9
	v_cndmask_b32_e32 v19, v205, v19, vcc
	v_lshlrev_b32_e32 v87, 2, v19
	v_xor_b32_e32 v19, 32, v205
	v_cmp_lt_i32_e32 vcc, v19, v18
	s_mul_i32 s8, s60, 9
	s_cmp_lt_i32 s100, 0
	s_cselect_b32 s40, 0x800, 0
	v_add_u32_e32 v68, s40, v65
	v_cndmask_b32_e32 v18, v205, v19, vcc
	v_lshlrev_b32_e32 v88, 2, v18
	v_mul_u32_u24_e32 v18, 0x90000, v17
	s_waitcnt lgkmcnt(0)
	v_lshl_add_u64 v[16:17], s[34:35], 0, v[192:193]
	v_lshlrev_b32_e32 v192, 1, v18
	v_lshl_add_u64 v[66:67], v[16:17], 0, v[192:193]
	s_mov_b64 s[34:35], 0
	s_branch .LBB0_142
.LBB0_141:
	s_or_b64 exec, exec, s[44:45]
	s_mul_i32 s40, s100, 3
	v_add_u32_e32 v68, s40, v68
	v_cmp_lt_i32_e32 vcc, s101, v68
	v_cmp_lt_i32_e64 s[40:41], v68, v65
	s_or_b64 vcc, vcc, s[40:41]
	s_or_b64 s[34:35], vcc, s[34:35]
	s_andn2_b64 exec, exec, s[34:35]
	s_cbranch_execz .LBB0_182
